# ping-pong attention loop: K-tile LDS write moved from the end of the matrix segment to the QK/PV boundary so its latency is covered by the PV MFMAs
# baseline (speedup 1.0000x reference)
; template <int KB>
; __device__ __forceinline__ void qkt(f32x16& p0, f32x16& p1, const char* K_lds, int r32, int hi, const bf16x8* qr) {
;     ...
;     for (int d0 = 0; d0 < 8; ++d0) { const char* a = kb[d0 & 3] + (d0 >> 2) * 128;
;         bf16x8 b0 = *reinterpret_cast<const bf16x8*>(a);
;         bf16x8 b1 = *reinterpret_cast<const bf16x8*>(a + 32 * 256);
;         p0 = __builtin_amdgcn_mfma_f32_32x32x16_bf16(b0, qr[d0], p0, 0, 0, 0);
;         p1 = __builtin_amdgcn_mfma_f32_32x32x16_bf16(b1, qr[d0], p1, 0, 0, 0); }
; }
; template <int VB>
; __device__ __forceinline__ void pv_tile(f32x16* o, int vb0, bf16x8 pa0, bf16x8 pa1, bf16x8 pa2, bf16x8 pa3) {
;     ...
;     PV_D0(0); PV_D0(1); PV_D0(2); PV_D0(3);
;     ...
; }
.Lp5_vw_a:
	global_load_dwordx2 v[146:147], v179, s[68:69] offset:-8
	s_add_u32 s98, s16, 0x40000
	s_addc_u32 s99, s17, 0
	global_load_dwordx4 v[130:133], v188, s[98:99]
	s_add_u32 s98, s16, 0x50000
	s_addc_u32 s99, s17, 0
	global_load_dwordx4 v[134:137], v188, s[98:99]
	ds_read_b128 v[66:69], v199 offset:49152
	ds_read_b128 v[82:85], v199 offset:57344
	ds_read_b128 v[172:175], v200 offset:49152
	ds_read_b128 v[232:235], v200 offset:57344
	ds_read_b128 v[236:239], v201 offset:49152
	ds_read_b128 v[240:243], v201 offset:57344
	ds_read_b128 v[244:247], v202 offset:49152
	s_waitcnt lgkmcnt(6)
	v_mfma_f32_32x32x16_bf16 v[66:81], v[66:69], v[126:129], 0
	s_waitcnt lgkmcnt(5)
	v_mfma_f32_32x32x16_bf16 v[82:97], v[82:85], v[126:129], 0
	s_waitcnt lgkmcnt(4)
	v_mfma_f32_32x32x16_bf16 v[66:81], v[172:175], v[122:125], v[66:81]
	ds_read_b128 v[172:175], v202 offset:57344
	s_waitcnt lgkmcnt(4)
	v_mfma_f32_32x32x16_bf16 v[82:97], v[232:235], v[122:125], v[82:97]
	ds_read_b128 v[232:235], v199 offset:49280
	s_waitcnt lgkmcnt(4)
	v_mfma_f32_32x32x16_bf16 v[66:81], v[236:239], v[118:121], v[66:81]
	ds_read_b128 v[236:239], v199 offset:57472
	s_waitcnt lgkmcnt(4)
	v_mfma_f32_32x32x16_bf16 v[82:97], v[240:243], v[118:121], v[82:97]
	ds_read_b128 v[240:243], v200 offset:49280
	s_waitcnt lgkmcnt(4)
	v_mfma_f32_32x32x16_bf16 v[66:81], v[244:247], v[114:117], v[66:81]
	ds_read_b128 v[244:247], v200 offset:57472
	s_waitcnt lgkmcnt(4)
	v_mfma_f32_32x32x16_bf16 v[82:97], v[172:175], v[114:117], v[82:97]
	ds_read_b128 v[172:175], v201 offset:49280
	s_waitcnt lgkmcnt(4)
	v_mfma_f32_32x32x16_bf16 v[66:81], v[232:235], v[110:113], v[66:81]
	ds_read_b128 v[232:235], v201 offset:57472
	s_waitcnt lgkmcnt(4)
	v_mfma_f32_32x32x16_bf16 v[82:97], v[236:239], v[110:113], v[82:97]
	ds_read_b128 v[236:239], v202 offset:49280
	s_waitcnt lgkmcnt(4)
	v_mfma_f32_32x32x16_bf16 v[66:81], v[240:243], v[106:109], v[66:81]
	ds_read_b64_tr_b16 v[212:213], v1 offset:0x0
	ds_read_b64_tr_b16 v[214:215], v1 offset:0x800
	ds_read_b64_tr_b16 v[216:217], v1 offset:0x200
	ds_read_b64_tr_b16 v[218:219], v1 offset:0xa00
	ds_read_b64_tr_b16 v[220:221], v1 offset:0x400
	ds_read_b64_tr_b16 v[222:223], v1 offset:0xc00
	ds_read_b64_tr_b16 v[224:225], v1 offset:0x600
	ds_read_b64_tr_b16 v[226:227], v1 offset:0xe00
	ds_read_b128 v[240:243], v202 offset:57472
	s_waitcnt lgkmcnt(12)
	v_mfma_f32_32x32x16_bf16 v[82:97], v[244:247], v[106:109], v[82:97]
	s_waitcnt lgkmcnt(11)
	v_mfma_f32_32x32x16_bf16 v[66:81], v[172:175], v[102:105], v[66:81]
	s_waitcnt lgkmcnt(10)
	v_mfma_f32_32x32x16_bf16 v[82:97], v[232:235], v[102:105], v[82:97]
	s_waitcnt lgkmcnt(9)
	v_mfma_f32_32x32x16_bf16 v[66:81], v[236:239], v[98:101], v[66:81]
	s_waitcnt lgkmcnt(0)
	v_mfma_f32_32x32x16_bf16 v[82:97], v[240:243], v[98:101], v[82:97]
	s_waitcnt vmcnt(3)
	ds_write_b128 v204, v[138:141] offset:32768
	ds_write_b128 v204, v[142:145] offset:40960
	ds_read_b64_tr_b16 v[248:249], v1 offset:0x1000
	ds_read_b64_tr_b16 v[250:251], v1 offset:0x1800
	ds_read_b64_tr_b16 v[172:173], v1 offset:0x1200
	ds_read_b64_tr_b16 v[174:175], v1 offset:0x1a00
	ds_read_b64_tr_b16 v[232:233], v1 offset:0x1400
	ds_read_b64_tr_b16 v[234:235], v1 offset:0x1c00
	s_waitcnt lgkmcnt(13)
	v_mfma_f32_32x32x16_bf16 v[2:17], v[148:151], v[212:215], v[2:17]
	ds_read_b64_tr_b16 v[236:237], v1 offset:0x1600
	ds_read_b64_tr_b16 v[238:239], v1 offset:0x1e00
	s_waitcnt lgkmcnt(13)
	v_mfma_f32_32x32x16_bf16 v[50:65], v[148:151], v[216:219], v[50:65]
	ds_read_b64_tr_b16 v[240:241], v1 offset:0x2000
	ds_read_b64_tr_b16 v[242:243], v1 offset:0x2800
	s_waitcnt lgkmcnt(13)
	v_mfma_f32_32x32x16_bf16 v[34:49], v[148:151], v[220:223], v[34:49]
	ds_read_b64_tr_b16 v[244:245], v1 offset:0x2200
	ds_read_b64_tr_b16 v[246:247], v1 offset:0x2a00
	s_waitcnt lgkmcnt(13)
	v_mfma_f32_32x32x16_bf16 v[18:33], v[148:151], v[224:227], v[18:33]
	ds_read_b64_tr_b16 v[224:225], v1 offset:0x2400
	ds_read_b64_tr_b16 v[226:227], v1 offset:0x2c00
	s_waitcnt lgkmcnt(12)
	v_mfma_f32_32x32x16_bf16 v[2:17], v[152:155], v[248:251], v[2:17]
	ds_read_b64_tr_b16 v[248:249], v1 offset:0x2600
	ds_read_b64_tr_b16 v[250:251], v1 offset:0x2e00
	s_waitcnt lgkmcnt(12)
	v_mfma_f32_32x32x16_bf16 v[50:65], v[152:155], v[172:175], v[50:65]
	ds_read_b64_tr_b16 v[172:173], v1 offset:0x3000
	ds_read_b64_tr_b16 v[174:175], v1 offset:0x3800
	s_waitcnt lgkmcnt(12)
	v_mfma_f32_32x32x16_bf16 v[34:49], v[152:155], v[232:235], v[34:49]
	ds_read_b64_tr_b16 v[232:233], v1 offset:0x3200
	ds_read_b64_tr_b16 v[234:235], v1 offset:0x3a00
	s_waitcnt lgkmcnt(12)
	v_mfma_f32_32x32x16_bf16 v[18:33], v[152:155], v[236:239], v[18:33]
	ds_read_b64_tr_b16 v[236:237], v1 offset:0x3400
	ds_read_b64_tr_b16 v[238:239], v1 offset:0x3c00
	s_waitcnt lgkmcnt(12)
	v_mfma_f32_32x32x16_bf16 v[2:17], v[156:159], v[240:243], v[2:17]
	ds_read_b64_tr_b16 v[240:241], v1 offset:0x3600
	ds_read_b64_tr_b16 v[242:243], v1 offset:0x3e00
	s_waitcnt lgkmcnt(12)
	v_mfma_f32_32x32x16_bf16 v[50:65], v[156:159], v[244:247], v[50:65]
	s_waitcnt lgkmcnt(10)
	v_mfma_f32_32x32x16_bf16 v[34:49], v[156:159], v[224:227], v[34:49]
	s_waitcnt lgkmcnt(8)
	v_mfma_f32_32x32x16_bf16 v[18:33], v[156:159], v[248:251], v[18:33]
	s_waitcnt lgkmcnt(6)
	v_mfma_f32_32x32x16_bf16 v[2:17], v[208:211], v[172:175], v[2:17]
	s_waitcnt lgkmcnt(4)
	v_mfma_f32_32x32x16_bf16 v[50:65], v[208:211], v[232:235], v[50:65]
	s_waitcnt lgkmcnt(2)
	v_mfma_f32_32x32x16_bf16 v[34:49], v[208:211], v[236:239], v[34:49]
	s_waitcnt lgkmcnt(0)
	v_mfma_f32_32x32x16_bf16 v[18:33], v[208:211], v[240:243], v[18:33]
	s_waitcnt lgkmcnt(0)
	s_barrier
	s_add_i32 s98, s82, 2
	s_cmp_gt_u32 s98, s81
	s_cbranch_scc1 .Lp5_k2_skip
	s_add_u32 s98, s100, 0x60000
	s_addc_u32 s99, s101, 0
	global_load_dwordx4 v[138:141], v188, s[98:99]
	s_add_u32 s98, s100, 0x70000
	s_addc_u32 s99, s101, 0
	global_load_dwordx4 v[142:145], v188, s[98:99]
	s_branch .Lp5_k2_done

; __device__ __forceinline__ void sel_mask_tile(f32x16& p0, f32x16& p1, unsigned wlo, unsigned whi, int hi) {
;     const unsigned NEGB = 0xff800000u;
;     const unsigned lo = wlo >> (4 * hi), h2 = whi >> (4 * hi);
; #pragma unroll
;     for (int r = 0; r < 16; ++r) {
;         const int c = (r & 3) + 8 * (r >> 2);
;         const unsigned m0 = (unsigned)__builtin_amdgcn_sbfe((int)lo, c, 1), m1 = (unsigned)__builtin_amdgcn_sbfe((int)h2, c, 1);
;         p0[r] = __uint_as_float((__float_as_uint(p0[r]) & m0) | (NEGB & ~m0));
;         p1[r] = __uint_as_float((__float_as_uint(p1[r]) & m1) | (NEGB & ~m1));
;     }
; }
; __device__ __forceinline__ void partialSM(f32x16& p0, f32x16& p1, float& m_reg, float& mn, float& alpha) {
;     float pmax = p0[0];
; #pragma unroll
;     for (int r = 1; r < 16; ++r) pmax = fmaxf(pmax, p0[r]);
; #pragma unroll
;     for (int r = 0; r < 16; ++r) pmax = fmaxf(pmax, p1[r]);
;     { auto rr = __builtin_amdgcn_permlane32_swap(__float_as_uint(pmax), __float_as_uint(pmax), false, false);
;       pmax = fmaxf(__uint_as_float(rr[0]), __uint_as_float(rr[1])); }
;     constexpr float C2 = 1.4426950408889634f * SCALE;
;     if (__builtin_expect(__all((pmax - m_reg) * SCALE <= THR), 1)) { mn = m_reg; alpha = 1.f; }
;     else { mn = fmaxf(m_reg, pmax); alpha = __builtin_amdgcn_exp2f((m_reg - mn) * C2); m_reg = mn; }
; template <int VB>
; __device__ __forceinline__ void pv_tile(f32x16* o, int vb0, bf16x8 pa0, bf16x8 pa1, bf16x8 pa2, bf16x8 pa3) {
;     ...
;     PV_D0(0); PV_D0(1); PV_D0(2); PV_D0(3);
;     ...
; }
.LBB0_1305:
	s_cmp_eq_u64 s[36:37], 0
	s_cbranch_scc1 .Lp5_kw2_skip
	s_waitcnt vmcnt(3)
	ds_write_b128 v204, v[138:141] offset:49152
	ds_write_b128 v204, v[142:145] offset:57344
.Lp5_kw2_skip:
	ds_read_b64_tr_b16 v[172:173], v1 offset:0x5000
	ds_read_b64_tr_b16 v[174:175], v1 offset:0x5800
	ds_read_b64_tr_b16 v[224:225], v1 offset:0x5200
	ds_read_b64_tr_b16 v[226:227], v1 offset:0x5a00
	ds_read_b64_tr_b16 v[232:233], v1 offset:0x5400
	ds_read_b64_tr_b16 v[234:235], v1 offset:0x5c00
	s_waitcnt lgkmcnt(12)
	v_mfma_f32_32x32x16_bf16 v[2:17], v[146:149], v[212:215], v[2:17]
	ds_read_b64_tr_b16 v[236:237], v1 offset:0x5600
	ds_read_b64_tr_b16 v[238:239], v1 offset:0x5e00
	s_waitcnt lgkmcnt(12)
	v_mfma_f32_32x32x16_bf16 v[50:65], v[146:149], v[216:219], v[50:65]
	ds_read_b64_tr_b16 v[240:241], v1 offset:0x6000
	ds_read_b64_tr_b16 v[242:243], v1 offset:0x6800
	s_waitcnt lgkmcnt(12)
	v_mfma_f32_32x32x16_bf16 v[34:49], v[146:149], v[220:223], v[34:49]
	ds_read_b64_tr_b16 v[244:245], v1 offset:0x6200
	ds_read_b64_tr_b16 v[246:247], v1 offset:0x6a00
	s_waitcnt lgkmcnt(12)
	v_mfma_f32_32x32x16_bf16 v[18:33], v[146:149], v[248:251], v[18:33]
	ds_read_b64_tr_b16 v[248:249], v1 offset:0x6400
	ds_read_b64_tr_b16 v[250:251], v1 offset:0x6c00
	s_waitcnt lgkmcnt(12)
	v_mfma_f32_32x32x16_bf16 v[2:17], v[150:153], v[172:175], v[2:17]
	ds_read_b64_tr_b16 v[172:173], v1 offset:0x6600
	ds_read_b64_tr_b16 v[174:175], v1 offset:0x6e00
	s_waitcnt lgkmcnt(12)
	v_mfma_f32_32x32x16_bf16 v[50:65], v[150:153], v[224:227], v[50:65]
	ds_read_b64_tr_b16 v[224:225], v1 offset:0x7000
	ds_read_b64_tr_b16 v[226:227], v1 offset:0x7800
	s_waitcnt lgkmcnt(12)
	v_mfma_f32_32x32x16_bf16 v[34:49], v[150:153], v[232:235], v[34:49]
	ds_read_b64_tr_b16 v[232:233], v1 offset:0x7200
	ds_read_b64_tr_b16 v[234:235], v1 offset:0x7a00
	s_waitcnt lgkmcnt(12)
	v_mfma_f32_32x32x16_bf16 v[18:33], v[150:153], v[236:239], v[18:33]
	ds_read_b64_tr_b16 v[236:237], v1 offset:0x7400
	ds_read_b64_tr_b16 v[238:239], v1 offset:0x7c00
	s_waitcnt lgkmcnt(12)
	v_mfma_f32_32x32x16_bf16 v[2:17], v[154:157], v[240:243], v[2:17]
	ds_read_b64_tr_b16 v[240:241], v1 offset:0x7600
	ds_read_b64_tr_b16 v[242:243], v1 offset:0x7e00
	s_waitcnt lgkmcnt(12)
	v_mfma_f32_32x32x16_bf16 v[50:65], v[154:157], v[244:247], v[50:65]
	s_waitcnt lgkmcnt(10)
	v_mfma_f32_32x32x16_bf16 v[34:49], v[154:157], v[248:251], v[34:49]
	s_waitcnt lgkmcnt(8)
	v_mfma_f32_32x32x16_bf16 v[18:33], v[154:157], v[172:175], v[18:33]
	s_waitcnt lgkmcnt(6)
	v_mfma_f32_32x32x16_bf16 v[2:17], v[158:161], v[224:227], v[2:17]
	s_waitcnt lgkmcnt(4)
	v_mfma_f32_32x32x16_bf16 v[50:65], v[158:161], v[232:235], v[50:65]
	s_waitcnt lgkmcnt(2)
	v_mfma_f32_32x32x16_bf16 v[34:49], v[158:161], v[236:239], v[34:49]
	s_waitcnt lgkmcnt(0)
	v_mfma_f32_32x32x16_bf16 v[18:33], v[158:161], v[240:243], v[18:33]
	s_waitcnt lgkmcnt(0)
	s_barrier
	s_nop 0
	s_waitcnt vmcnt(2)
	v_lshrrev_b32_e32 v193, v163, v228
	v_bfe_i32 v192, v193, 0, 1
	v_bitop3_b32 v192, v82, s74, v192 bitop3:0xe4
	v_bfe_i32 v82, v193, 1, 1
	v_bitop3_b32 v146, v83, s74, v82 bitop3:0xe4
	v_bfe_i32 v82, v193, 2, 1
	v_bitop3_b32 v147, v84, s74, v82 bitop3:0xe4
	v_bfe_i32 v82, v193, 3, 1
	v_bitop3_b32 v148, v85, s74, v82 bitop3:0xe4
	v_bfe_i32 v82, v193, 8, 1
	v_bitop3_b32 v149, v86, s74, v82 bitop3:0xe4
	v_bfe_i32 v82, v193, 9, 1
	v_bitop3_b32 v150, v87, s74, v82 bitop3:0xe4
	v_bfe_i32 v82, v193, 10, 1
	v_bitop3_b32 v88, v88, s74, v82 bitop3:0xe4
	v_bfe_i32 v82, v193, 11, 1
	v_bitop3_b32 v89, v89, s74, v82 bitop3:0xe4
	v_bfe_i32 v82, v193, 16, 1
	v_bitop3_b32 v90, v90, s74, v82 bitop3:0xe4
	v_bfe_i32 v82, v193, 17, 1
	v_bitop3_b32 v91, v91, s74, v82 bitop3:0xe4
	v_bfe_i32 v82, v193, 18, 1
	v_bitop3_b32 v92, v92, s74, v82 bitop3:0xe4
	v_bfe_i32 v82, v193, 19, 1
	v_bitop3_b32 v93, v93, s74, v82 bitop3:0xe4
	v_bfe_i32 v82, v193, 24, 1
	v_bitop3_b32 v94, v94, s74, v82 bitop3:0xe4
	v_bfe_i32 v82, v193, 25, 1
	v_bitop3_b32 v95, v95, s74, v82 bitop3:0xe4
	v_bfe_i32 v82, v193, 26, 1
	v_bitop3_b32 v96, v96, s74, v82 bitop3:0xe4
	v_bfe_i32 v82, v193, 27, 1
	v_bitop3_b32 v97, v97, s74, v82 bitop3:0xe4
	v_max_f32_e32 v82, v192, v146
	v_max3_f32 v82, v82, v147, v148
	v_max3_f32 v82, v82, v149, v150
	v_max3_f32 v82, v82, v88, v89
	v_max3_f32 v82, v82, v90, v91
	v_lshrrev_b32_e32 v194, v163, v229
	v_max3_f32 v82, v82, v92, v93
	v_bfe_i32 v195, v194, 0, 1
	v_bfe_i32 v172, v194, 1, 1
	v_max3_f32 v82, v82, v94, v95
	v_bitop3_b32 v66, v66, s74, v195 bitop3:0xe4
	v_bfe_i32 v83, v194, 2, 1
	v_bfe_i32 v84, v194, 3, 1
	v_max3_f32 v230, v82, v96, v97
	v_bitop3_b32 v67, v67, s74, v172 bitop3:0xe4
	v_bfe_i32 v85, v194, 8, 1
	v_bfe_i32 v86, v194, 9, 1
	v_bitop3_b32 v82, v68, s74, v83 bitop3:0xe4
	v_max3_f32 v68, v230, v66, v67
	v_bitop3_b32 v83, v69, s74, v84 bitop3:0xe4
	v_bfe_i32 v87, v194, 10, 1
	v_bfe_i32 v151, v194, 11, 1
	v_bitop3_b32 v84, v70, s74, v85 bitop3:0xe4
	v_max3_f32 v68, v68, v82, v83
	v_bitop3_b32 v85, v71, s74, v86 bitop3:0xe4
	v_bfe_i32 v152, v194, 16, 1
	v_bfe_i32 v153, v194, 17, 1
	v_bitop3_b32 v86, v72, s74, v87 bitop3:0xe4
	v_max3_f32 v68, v68, v84, v85
	v_bitop3_b32 v87, v73, s74, v151 bitop3:0xe4
	v_bfe_i32 v154, v194, 18, 1
	v_bfe_i32 v155, v194, 19, 1
	v_bitop3_b32 v74, v74, s74, v152 bitop3:0xe4
	v_max3_f32 v69, v68, v86, v87
	v_bitop3_b32 v75, v75, s74, v153 bitop3:0xe4
	v_bfe_i32 v156, v194, 24, 1
	v_bfe_i32 v157, v194, 25, 1
	v_bitop3_b32 v68, v76, s74, v154 bitop3:0xe4
	v_max3_f32 v71, v69, v74, v75
	v_bitop3_b32 v69, v77, s74, v155 bitop3:0xe4
	v_bfe_i32 v230, v194, 26, 1
	v_bfe_i32 v231, v194, 27, 1
	v_bitop3_b32 v70, v78, s74, v156 bitop3:0xe4
	v_max3_f32 v73, v71, v68, v69
	v_bitop3_b32 v71, v79, s74, v157 bitop3:0xe4
	v_bitop3_b32 v72, v80, s74, v230 bitop3:0xe4
	v_max3_f32 v76, v73, v70, v71
	v_bitop3_b32 v73, v81, s74, v231 bitop3:0xe4
	v_max3_f32 v76, v76, v72, v73
	v_mov_b32_e32 v77, v76
	s_nop 1
	v_permlane32_swap_b32_e32 v76, v77
	v_max_f32_e32 v76, v76, v77
	v_sub_f32_e32 v77, v76, v206
	v_mul_f32_e32 v77, 0x3db504f3, v77
	v_cmp_ge_f32_e32 vcc, s75, v77
	s_cmp_eq_u64 vcc, exec
	s_cselect_b64 s[6:7], -1, 0
